# attention: next-tile K/V LDS-DMA issue moved from the loop top into the softmax VALU section
# speedup vs baseline: 1.0052x; 1.0052x over previous
; #define LAS __attribute__((address_space(3)))
; __device__ __forceinline__ float xor16_max(float v) { float a = v, b = v; swap16(a, b); return fmaxf(a, b); }
; template <int DQK, int QF>
; __device__ __forceinline__ void attn_unit_dma(LAS unsigned char* lds, const bf16_t* Qp, int ldq, const bf16_t* Kp, int ldk, const bf16_t* VTp, int ldvt, bf16_t* Op, int ldo, int nkt, int wave_last, const float* qgam, float qscale) {
;     ...
;     for (int t = 0; t < nkt; ++t) {
;         const int s2slot = (slot == 0) ? 2 : slot - 1;
;         if (t + 2 < nkt) AT_DMA(t + 2, s2slot);
;         if (t <= wave_last) {
;             const LAS unsigned char* kb = lds + slot * BUF; const LAS unsigned char* vb = kb + KBYTES;
;             f32x4 st[QF][4];
; #pragma unroll
;             for (int qf = 0; qf < QF; ++qf)
; #pragma unroll
;                 for (int m = 0; m < 4; ++m) st[qf][m] = (f32x4){0.f, 0.f, 0.f, 0.f};
;             {
;                 bf16x8 kf[2][4];
; #pragma unroll
;                 for (int m = 0; m < 4; ++m) kf[0][m] = *(const LAS bf16x8*)(kb + (16 * m + fr) * KROW + fq * 16);
; #pragma unroll
;                 for (int s = 0; s < KS; ++s) {
;                     if (s + 1 < KS) {
; #pragma unroll
;                         for (int m = 0; m < 4; ++m) kf[(s + 1) & 1][m] = *(const LAS bf16x8*)(kb + (16 * m + fr) * KROW + (s + 1) * 64 + fq * 16);
;                     }
;                     __builtin_amdgcn_sched_group_barrier(0x100, 4, 0);
;                     __builtin_amdgcn_sched_group_barrier(0x008, 4 * QF, 0);
; #pragma unroll
;                     for (int m = 0; m < 4; ++m)
; #pragma unroll
;                         for (int qf = 0; qf < QF; ++qf) st[qf][m] = __builtin_amdgcn_mfma_f32_16x16x32_bf16(kf[s & 1][m], qreg[qf][s], st[qf][m], 0, 0, 0);
;                 }
;             }
;             bf16x8 pb[QF][2];
; #pragma unroll
;             for (int qf = 0; qf < QF; ++qf) {
;                 float mx = st[qf][0][0];
; #pragma unroll
;                 for (int m = 0; m < 4; ++m)
; #pragma unroll
;                     for (int j = 0; j < 4; ++j) mx = fmaxf(mx, st[qf][m][j]);
;                 mx = xor16_max(mx); mx = xor32_max(mx);
;                 const float mnew = fmaxf(mrun[qf], mx), alpha = __builtin_amdgcn_exp2f(mrun[qf] - mnew);
;                 mrun[qf] = mnew;
.LBB0_1099:
	s_add_i32 s12, s35, 2
	s_cmp_ge_i32 s12, s0
	s_cselect_b64 s[70:71], -1, 0
	s_and_b64 vcc, exec, s[70:71]
	s_mul_i32 s12, s34, 0xa000
	s_cbranch_vccnz .LBB0_1107
	s_add_i32 s13, s12, 0xffff6000
	s_cmp_lg_u32 s34, 0
	s_cselect_b32 s13, s13, 0x14000
	s_add_i32 s13, s13, s97
.LBB0_1107:
	s_cmp_gt_i32 s35, s95
	s_cbranch_scc1 .Latt_masked
	s_add_i32 s12, s12, 0
	v_add_u32_e32 v113, s12, v204
	ds_read_b128 v[114:117], v113
	ds_read_b128 v[118:121], v113 offset:1024
	ds_read_b128 v[122:125], v113 offset:2048
	ds_read_b128 v[130:133], v113 offset:3072
	ds_read_b128 v[134:137], v113 offset:4096
	ds_read_b128 v[138:141], v113 offset:5120
	ds_read_b128 v[142:145], v113 offset:6144
	ds_read_b128 v[146:149], v113 offset:7168
	s_waitcnt lgkmcnt(4)
	v_mfma_f32_16x16x32_bf16 v[150:153], v[114:117], v[0:3], 0
	v_mfma_f32_16x16x32_bf16 v[114:117], v[114:117], v[24:27], 0
	v_mfma_f32_16x16x32_bf16 v[154:157], v[118:121], v[0:3], 0
	v_mfma_f32_16x16x32_bf16 v[118:121], v[118:121], v[24:27], 0
	v_mfma_f32_16x16x32_bf16 v[158:161], v[122:125], v[0:3], 0
	v_mfma_f32_16x16x32_bf16 v[122:125], v[122:125], v[24:27], 0
	v_mfma_f32_16x16x32_bf16 v[162:165], v[130:133], v[0:3], 0
	v_mfma_f32_16x16x32_bf16 v[130:133], v[130:133], v[24:27], 0
	ds_read_b128 v[166:169], v113 offset:8192
	ds_read_b128 v[170:173], v113 offset:9216
	ds_read_b128 v[174:177], v113 offset:10240
	ds_read_b128 v[178:181], v113 offset:11264
	s_waitcnt lgkmcnt(4)
	v_mfma_f32_16x16x32_bf16 v[150:153], v[134:137], v[4:7], v[150:153]
	v_mfma_f32_16x16x32_bf16 v[114:117], v[134:137], v[28:31], v[114:117]
	v_mfma_f32_16x16x32_bf16 v[134:137], v[138:141], v[4:7], v[154:157]
	v_mfma_f32_16x16x32_bf16 v[118:121], v[138:141], v[28:31], v[118:121]
	v_mfma_f32_16x16x32_bf16 v[138:141], v[142:145], v[4:7], v[158:161]
	v_mfma_f32_16x16x32_bf16 v[122:125], v[142:145], v[28:31], v[122:125]
	v_mfma_f32_16x16x32_bf16 v[142:145], v[146:149], v[4:7], v[162:165]
	v_mfma_f32_16x16x32_bf16 v[130:133], v[146:149], v[28:31], v[130:133]
	ds_read_b128 v[146:149], v113 offset:12288
	ds_read_b128 v[154:157], v113 offset:13312
	ds_read_b128 v[158:161], v113 offset:14336
	ds_read_b128 v[162:165], v113 offset:15360
	s_waitcnt lgkmcnt(4)
	v_mfma_f32_16x16x32_bf16 v[150:153], v[166:169], v[8:11], v[150:153]
	v_mfma_f32_16x16x32_bf16 v[114:117], v[166:169], v[32:35], v[114:117]
	v_mfma_f32_16x16x32_bf16 v[134:137], v[170:173], v[8:11], v[134:137]
	v_mfma_f32_16x16x32_bf16 v[118:121], v[170:173], v[32:35], v[118:121]
	v_mfma_f32_16x16x32_bf16 v[138:141], v[174:177], v[8:11], v[138:141]
	v_mfma_f32_16x16x32_bf16 v[122:125], v[174:177], v[32:35], v[122:125]
	v_mfma_f32_16x16x32_bf16 v[142:145], v[178:181], v[8:11], v[142:145]
	v_mfma_f32_16x16x32_bf16 v[130:133], v[178:181], v[32:35], v[130:133]
	ds_read_b128 v[166:169], v113 offset:16384
	ds_read_b128 v[170:173], v113 offset:17408
	ds_read_b128 v[174:177], v113 offset:18432
	ds_read_b128 v[178:181], v113 offset:19456
	s_waitcnt lgkmcnt(4)
	v_mfma_f32_16x16x32_bf16 v[150:153], v[146:149], v[12:15], v[150:153]
	v_mfma_f32_16x16x32_bf16 v[114:117], v[146:149], v[36:39], v[114:117]
	v_mfma_f32_16x16x32_bf16 v[134:137], v[154:157], v[12:15], v[134:137]
	v_mfma_f32_16x16x32_bf16 v[118:121], v[154:157], v[36:39], v[118:121]
	v_mfma_f32_16x16x32_bf16 v[138:141], v[158:161], v[12:15], v[138:141]
	v_mfma_f32_16x16x32_bf16 v[122:125], v[158:161], v[36:39], v[122:125]
	v_mfma_f32_16x16x32_bf16 v[142:145], v[162:165], v[12:15], v[142:145]
	v_mfma_f32_16x16x32_bf16 v[130:133], v[162:165], v[36:39], v[130:133]
	ds_read_b128 v[146:149], v113 offset:20480
	ds_read_b128 v[154:157], v113 offset:21504
	ds_read_b128 v[158:161], v113 offset:22528
	ds_read_b128 v[162:165], v113 offset:23552
	s_waitcnt lgkmcnt(4)
	v_mfma_f32_16x16x32_bf16 v[150:153], v[166:169], v[16:19], v[150:153]
	v_mfma_f32_16x16x32_bf16 v[114:117], v[166:169], v[40:43], v[114:117]
	v_mfma_f32_16x16x32_bf16 v[134:137], v[170:173], v[16:19], v[134:137]
	v_mfma_f32_16x16x32_bf16 v[118:121], v[170:173], v[40:43], v[118:121]
	v_mfma_f32_16x16x32_bf16 v[138:141], v[174:177], v[16:19], v[138:141]
	v_mfma_f32_16x16x32_bf16 v[122:125], v[174:177], v[40:43], v[122:125]
	v_mfma_f32_16x16x32_bf16 v[142:145], v[178:181], v[16:19], v[142:145]
	v_mfma_f32_16x16x32_bf16 v[130:133], v[178:181], v[40:43], v[130:133]
	s_waitcnt lgkmcnt(0)
	v_mfma_f32_16x16x32_bf16 v[150:153], v[146:149], v[20:23], v[150:153]
	v_mfma_f32_16x16x32_bf16 v[146:149], v[146:149], v[44:47], v[114:117]
	v_mfma_f32_16x16x32_bf16 v[114:117], v[154:157], v[20:23], v[134:137]
	s_nop 5
	v_max_f32_e32 v113, v151, v151
	v_max_f32_e32 v126, v150, v150
	v_max_f32_e32 v113, v126, v113
	v_mfma_f32_16x16x32_bf16 v[134:137], v[154:157], v[44:47], v[118:121]
	v_max3_f32 v113, v113, v152, v153
	v_max3_f32 v113, v113, v114, v115
	v_max3_f32 v113, v113, v116, v117
	v_mfma_f32_16x16x32_bf16 v[118:121], v[158:161], v[20:23], v[138:141]
	v_mfma_f32_16x16x32_bf16 v[138:141], v[158:161], v[44:47], v[122:125]
	v_mfma_f32_16x16x32_bf16 v[122:125], v[162:165], v[20:23], v[142:145]
	s_nop 5
	v_max3_f32 v113, v113, v118, v119
	v_max3_f32 v113, v113, v120, v121
	v_mfma_f32_16x16x32_bf16 v[130:133], v[162:165], v[44:47], v[130:133]
	v_max3_f32 v113, v113, v122, v123
	v_max3_f32 v113, v113, v124, v125
	v_mov_b32_e32 v126, v113
	s_nop 1
	v_permlane16_swap_b32 v113, v126
	s_nop 0
	v_max_f32_e32 v126, v126, v126
	v_max_f32_e32 v113, v113, v113
	v_max_f32_e32 v113, v113, v126
	v_mov_b32_e32 v126, v113
	s_nop 1
	v_permlane32_swap_b32 v113, v126
	s_nop 0
	v_max3_f32 v220, v112, v113, v126
	v_sub_f32_e32 v113, v150, v220
	v_exp_f32_e32 v143, v113
	v_sub_f32_e32 v113, v151, v220
	v_sub_f32_e32 v112, v112, v220
	v_exp_f32_e32 v145, v113
	s_cbranch_vccnz .Latt_nd0
	s_add_u32 s84, s86, s68
	s_addc_u32 s85, s87, s69
	s_mov_b32 m0, s13
	s_nop 0
	global_load_lds_dwordx4 v200, s[84:85]
; __device__ __forceinline__ unsigned pk2(float lo, float hi) { f32x2_t v = {lo, hi}; bf16x2_t b = __builtin_convertvector(v, bf16x2_t); return __builtin_bit_cast(unsigned, b); }
; __device__ __forceinline__ float xor16_max(float v) { float a = v, b = v; swap16(a, b); return fmaxf(a, b); }
; __device__ __forceinline__ float xor32_max(float v) { float a = v, b = v; swap32(a, b); return fmaxf(a, b); }
; template <int DQK, int QF>
; __device__ __forceinline__ void attn_unit_dma(LAS unsigned char* lds, const bf16_t* Qp, int ldq, const bf16_t* Kp, int ldk, const bf16_t* VTp, int ldvt, bf16_t* Op, int ldo, int nkt, int wave_last, const float* qgam, float qscale) {
;     ...
;                 mx = xor16_max(mx); mx = xor32_max(mx);
;                 const float mnew = fmaxf(mrun[qf], mx), alpha = __builtin_amdgcn_exp2f(mrun[qf] - mnew);
;                 mrun[qf] = mnew;
;                 float ps = 0.f; float p[4][4];
; #pragma unroll
;                 for (int m = 0; m < 4; ++m)
; #pragma unroll
;                     for (int j = 0; j < 4; ++j) { p[m][j] = __builtin_amdgcn_exp2f(st[qf][m][j] - mnew); ps += p[m][j]; }
;                 lrun[qf] = lrun[qf] * alpha + ps;
; #pragma unroll
;                 for (int mv = 0; mv < 8; ++mv) o[qf][mv] = o[qf][mv] * alpha;
; #pragma unroll
;                 for (int s2 = 0; s2 < 2; ++s2) {
;                     u32x4 w; w.x = pk2(p[2 * s2][0], p[2 * s2][1]); w.y = pk2(p[2 * s2][2], p[2 * s2][3]); w.z = pk2(p[2 * s2 + 1][0], p[2 * s2 + 1][1]); w.w = pk2(p[2 * s2 + 1][2], p[2 * s2 + 1][3]);
;                     pb[qf][s2] = __builtin_bit_cast(bf16x8, w);
;                 }
;             }
;             {
;                 u32x2 vr[2][4][2];
.Latt_nd0:
	v_sub_f32_e32 v113, v152, v220
	v_exp_f32_e32 v151, v113
	v_sub_f32_e32 v113, v153, v220
	v_exp_f32_e32 v178, v112
	v_exp_f32_e32 v153, v113
	s_cbranch_vccnz .Latt_nd1
	s_add_i32 m0, s13, 0x1f80
	s_nop 0
	global_load_lds_dwordx4 v200, s[84:85] offset:128
.Latt_nd1:
	v_sub_f32_e32 v113, v114, v220
	v_exp_f32_e32 v155, v113
	v_sub_f32_e32 v113, v115, v220
	v_exp_f32_e32 v157, v113
	v_sub_f32_e32 v113, v116, v220
	v_exp_f32_e32 v159, v113
	s_cbranch_vccnz .Latt_nd2
	s_add_i32 m0, s13, 0x3f00
	s_nop 0
	global_load_lds_dwordx4 v200, s[84:85] offset:256
.Latt_nd2:
	v_sub_f32_e32 v113, v117, v220
	v_pk_mul_f32 v[116:117], v[92:93], v[178:179] op_sel_hi:[1,0]
	v_pk_mul_f32 v[92:93], v[104:105], v[178:179] op_sel_hi:[1,0]
	v_max_f32_e32 v104, v147, v147
	v_max_f32_e32 v105, v146, v146
	v_max_f32_e32 v104, v105, v104
	v_max3_f32 v104, v104, v148, v149
	v_max3_f32 v104, v104, v134, v135
	v_max3_f32 v104, v104, v136, v137
	v_max3_f32 v104, v104, v138, v139
	v_max3_f32 v104, v104, v140, v141
	v_max3_f32 v104, v104, v130, v131
	v_max3_f32 v104, v104, v132, v133
	v_mov_b32_e32 v105, v104
	s_nop 1
	v_permlane16_swap_b32 v104, v105
	v_exp_f32_e32 v161, v113
	v_max_f32_e32 v105, v105, v105
	v_max_f32_e32 v104, v104, v104
	v_max_f32_e32 v104, v104, v105
	v_mov_b32_e32 v105, v104
	s_nop 1
	v_permlane32_swap_b32 v104, v105
	v_sub_f32_e32 v113, v118, v220
	v_max3_f32 v221, v128, v104, v105
	v_sub_f32_e32 v104, v146, v221
	v_exp_f32_e32 v142, v104
	s_cbranch_vccnz .Latt_nd3
	s_add_u32 s84, s86, s66
	s_addc_u32 s85, s87, s67
	s_add_i32 m0, s13, 0x6000
	s_nop 0
	global_load_lds_dwordx4 v202, s[84:85]
.Latt_nd3:
	v_sub_f32_e32 v104, v147, v221
	v_exp_f32_e32 v144, v104
	v_sub_f32_e32 v104, v148, v221
	v_exp_f32_e32 v150, v104
	s_cbranch_vccnz .Latt_nd4
	s_add_i32 m0, s13, 0x7fc0
	s_nop 0
	global_load_lds_dwordx4 v202, s[84:85] offset:64
.Latt_nd4:
	v_sub_f32_e32 v104, v149, v221
	v_exp_f32_e32 v152, v104
	v_sub_f32_e32 v104, v134, v221
	v_exp_f32_e32 v154, v104
	v_sub_f32_e32 v104, v135, v221
	v_exp_f32_e32 v156, v104
	v_sub_f32_e32 v104, v136, v221
	v_exp_f32_e32 v158, v104
	v_pk_add_f32 v[104:105], v[142:143], 0 op_sel_hi:[1,0]
	v_exp_f32_e32 v163, v113
	v_pk_add_f32 v[104:105], v[144:145], v[104:105]
	v_sub_f32_e32 v113, v119, v220
	v_pk_mul_f32 v[118:119], v[94:95], v[178:179] op_sel_hi:[1,0]
	v_pk_mul_f32 v[94:95], v[106:107], v[178:179] op_sel_hi:[1,0]
	v_pk_add_f32 v[104:105], v[150:151], v[104:105]
	v_sub_f32_e32 v107, v137, v221
	v_pk_add_f32 v[104:105], v[152:153], v[104:105]
	v_exp_f32_e32 v160, v107
	v_sub_f32_e32 v107, v138, v221
	v_pk_add_f32 v[104:105], v[154:155], v[104:105]
	v_exp_f32_e32 v162, v107
	v_sub_f32_e32 v107, v139, v221
	v_exp_f32_e32 v165, v113
	v_sub_f32_e32 v113, v120, v220
	v_pk_add_f32 v[104:105], v[156:157], v[104:105]
	v_exp_f32_e32 v164, v107
	v_sub_f32_e32 v107, v140, v221
	v_exp_f32_e32 v167, v113
	v_sub_f32_e32 v113, v121, v220
	v_pk_add_f32 v[104:105], v[158:159], v[104:105]
	v_exp_f32_e32 v166, v107
	v_sub_f32_e32 v107, v141, v221
	v_exp_f32_e32 v169, v113
	v_sub_f32_e32 v113, v122, v220
	v_exp_f32_e32 v168, v107
	v_sub_f32_e32 v107, v130, v221
	v_pk_add_f32 v[104:105], v[160:161], v[104:105]
	v_exp_f32_e32 v171, v113
	v_sub_f32_e32 v113, v123, v220
	v_exp_f32_e32 v170, v107
	v_sub_f32_e32 v107, v131, v221
	v_pk_add_f32 v[104:105], v[162:163], v[104:105]
	v_exp_f32_e32 v173, v113
	v_sub_f32_e32 v113, v124, v220
	v_exp_f32_e32 v172, v107
	v_sub_f32_e32 v107, v132, v221
	v_pk_add_f32 v[104:105], v[164:165], v[104:105]
	v_exp_f32_e32 v175, v113
	v_sub_f32_e32 v113, v125, v220
	v_exp_f32_e32 v174, v107
	v_sub_f32_e32 v107, v133, v221
	v_pk_add_f32 v[104:105], v[166:167], v[104:105]
	v_exp_f32_e32 v177, v113
	v_sub_f32_e32 v106, v128, v221
	v_exp_f32_e32 v176, v107
	v_pk_add_f32 v[104:105], v[168:169], v[104:105]
	v_exp_f32_e32 v136, v106
	v_pk_add_f32 v[104:105], v[170:171], v[104:105]
	v_mov_b32_e32 v137, v178
	v_pk_add_f32 v[104:105], v[172:173], v[104:105]
	v_pk_mul_f32 v[126:127], v[98:99], v[178:179] op_sel_hi:[1,0]
	v_pk_add_f32 v[104:105], v[174:175], v[104:105]
	v_pk_mul_f32 v[124:125], v[96:97], v[178:179] op_sel_hi:[1,0]
	v_pk_add_f32 v[104:105], v[176:177], v[104:105]
	v_pk_mul_f32 v[98:99], v[90:91], v[178:179] op_sel_hi:[1,0]
	v_pk_mul_f32 v[96:97], v[88:89], v[178:179] op_sel_hi:[1,0]
	v_pk_mul_f32 v[90:91], v[110:111], v[178:179] op_sel_hi:[1,0]
	v_pk_mul_f32 v[88:89], v[108:109], v[178:179] op_sel_hi:[1,0]
	v_pk_fma_f32 v[206:207], v[206:207], v[136:137], v[104:105]
	v_pk_mul_f32 v[134:135], v[70:71], v[136:137] op_sel_hi:[1,0]
	v_pk_mul_f32 v[132:133], v[68:69], v[136:137] op_sel_hi:[1,0]
	v_pk_mul_f32 v[130:131], v[66:67], v[136:137] op_sel_hi:[1,0]
	v_pk_mul_f32 v[128:129], v[64:65], v[136:137] op_sel_hi:[1,0]
	v_pk_mul_f32 v[110:111], v[62:63], v[136:137] op_sel_hi:[1,0]
	v_pk_mul_f32 v[108:109], v[60:61], v[136:137] op_sel_hi:[1,0]
	v_pk_mul_f32 v[106:107], v[58:59], v[136:137] op_sel_hi:[1,0]
	v_pk_mul_f32 v[104:105], v[56:57], v[136:137] op_sel_hi:[1,0]
	v_pk_mul_f32 v[70:71], v[74:75], v[136:137] op_sel_hi:[1,0]
	v_pk_mul_f32 v[68:69], v[72:73], v[136:137] op_sel_hi:[1,0]
	v_pk_mul_f32 v[66:67], v[78:79], v[136:137] op_sel_hi:[1,0]
	v_pk_mul_f32 v[64:65], v[76:77], v[136:137] op_sel_hi:[1,0]
	v_pk_mul_f32 v[62:63], v[82:83], v[136:137] op_sel_hi:[1,0]
	v_pk_mul_f32 v[60:61], v[80:81], v[136:137] op_sel_hi:[1,0]
	v_pk_mul_f32 v[58:59], v[54:55], v[136:137] op_sel_hi:[1,0]
	v_pk_mul_f32 v[56:57], v[52:53], v[136:137] op_sel_hi:[1,0]
	v_add_u32_e32 v222, s12, v204
	v_pk_mul_f32 v[112:113], v[84:85], v[178:179] op_sel_hi:[1,0]
	v_pk_mul_f32 v[84:85], v[48:49], v[178:179] op_sel_hi:[1,0]
	v_cvt_pk_bf16_f32 v48, v163, v165
	v_cvt_pk_bf16_f32 v49, v167, v169
	v_cvt_pk_bf16_f32 v52, v162, v164
	v_cvt_pk_bf16_f32 v53, v166, v168
	v_pk_mul_f32 v[122:123], v[102:103], v[178:179] op_sel_hi:[1,0]
	v_pk_mul_f32 v[120:121], v[100:101], v[178:179] op_sel_hi:[1,0]
	v_cvt_pk_bf16_f32 v100, v143, v145
	v_cvt_pk_bf16_f32 v101, v151, v153
	v_cvt_pk_bf16_f32 v102, v155, v157
	v_cvt_pk_bf16_f32 v103, v159, v161
	v_cvt_pk_bf16_f32 v72, v142, v144
	v_cvt_pk_bf16_f32 v73, v150, v152
	v_cvt_pk_bf16_f32 v74, v154, v156
	v_cvt_pk_bf16_f32 v75, v158, v160
	ds_read_b128 v[76:79], v222 offset:24576
	ds_read_b128 v[80:83], v222 offset:25600
	ds_read_b128 v[156:159], v222 offset:26624
	ds_read_b128 v[160:163], v222 offset:27648
	ds_read_b128 v[140:143], v222 offset:28672
	ds_read_b128 v[144:147], v222 offset:29696
	ds_read_b128 v[148:151], v222 offset:30720
	ds_read_b128 v[152:155], v222 offset:31744
	v_pk_mul_f32 v[114:115], v[86:87], v[178:179] op_sel_hi:[1,0]
	v_pk_mul_f32 v[86:87], v[50:51], v[178:179] op_sel_hi:[1,0]
	v_cvt_pk_bf16_f32 v50, v171, v173
	v_cvt_pk_bf16_f32 v51, v175, v177
	v_cvt_pk_bf16_f32 v54, v170, v172
	v_cvt_pk_bf16_f32 v55, v174, v176
	s_waitcnt lgkmcnt(4)
; #define AT_VLOAD(buf_, grp_) do { _Pragma("unroll") for (int i = 0; i < 4; ++i) { const int s2_ = (grp_) >> 1, mv_ = ((grp_) & 1) * 4 + i; \
;                     const LAS unsigned char* vp = vb + (16 * mv_ + fr) * VROW + (32 * s2_ + 4 * fq) * 2; \
;                     vr[buf_][i][0] = *(const LAS u32x2*)vp; vr[buf_][i][1] = *(const LAS u32x2*)(vp + 32); } } while (0)
; template <int DQK, int QF>
; __device__ __forceinline__ void attn_unit_dma(LAS unsigned char* lds, const bf16_t* Qp, int ldq, const bf16_t* Kp, int ldk, const bf16_t* VTp, int ldvt, bf16_t* Op, int ldo, int nkt, int wave_last, const float* qgam, float qscale) {
;     ...
;                 AT_VLOAD(0, 0);
; #pragma unroll
;                 for (int grp = 0; grp < 4; ++grp) {
;                     if (grp + 1 < 4) AT_VLOAD((grp + 1) & 1, grp + 1);
;                     __builtin_amdgcn_sched_group_barrier(0x100, 8, 0);
;                     __builtin_amdgcn_sched_group_barrier(0x008, 4 * QF, 0);
; #pragma unroll
;                     for (int i = 0; i < 4; ++i) {
;                         const int s2 = grp >> 1, mv = (grp & 1) * 4 + i;
;                         u32x4 vv; vv.x = vr[grp & 1][i][0].x; vv.y = vr[grp & 1][i][0].y; vv.z = vr[grp & 1][i][1].x; vv.w = vr[grp & 1][i][1].y;
;                         const bf16x8 vf = __builtin_bit_cast(bf16x8, vv);
; #pragma unroll
;                         for (int qf = 0; qf < QF; ++qf) o[qf][mv] = __builtin_amdgcn_mfma_f32_16x16x32_bf16(vf, pb[qf][s2], o[qf][mv], 0, 0, 0);
;                     }
;                 }
;     ...
;             }
;         }
	v_mfma_f32_16x16x32_bf16 v[136:139], v[76:79], v[100:103], v[124:127]
	v_mfma_f32_16x16x32_bf16 v[132:135], v[76:79], v[72:75], v[132:135]
	v_mfma_f32_16x16x32_bf16 v[120:123], v[80:83], v[100:103], v[120:123]
	v_mfma_f32_16x16x32_bf16 v[124:127], v[80:83], v[72:75], v[128:131]
	v_mfma_f32_16x16x32_bf16 v[116:119], v[156:159], v[100:103], v[116:119]
	v_mfma_f32_16x16x32_bf16 v[108:111], v[156:159], v[72:75], v[108:111]
	v_mfma_f32_16x16x32_bf16 v[76:79], v[160:163], v[100:103], v[112:115]
	v_mfma_f32_16x16x32_bf16 v[80:83], v[160:163], v[72:75], v[104:107]
	ds_read_b128 v[180:183], v222 offset:32768
	ds_read_b128 v[176:179], v222 offset:33792
	ds_read_b128 v[172:175], v222 offset:34816
	ds_read_b128 v[168:171], v222 offset:35840
	ds_read_b128 v[226:229], v222 offset:38912
	s_waitcnt lgkmcnt(5)
	v_mfma_f32_16x16x32_bf16 v[164:167], v[140:143], v[100:103], v[96:99]
	v_mfma_f32_16x16x32_bf16 v[160:163], v[140:143], v[72:75], v[68:71]
	v_mfma_f32_16x16x32_bf16 v[104:107], v[144:147], v[100:103], v[92:95]
	v_mfma_f32_16x16x32_bf16 v[156:159], v[144:147], v[72:75], v[64:67]
	v_mfma_f32_16x16x32_bf16 v[144:147], v[148:151], v[100:103], v[88:91]
	v_mfma_f32_16x16x32_bf16 v[140:143], v[148:151], v[72:75], v[60:63]
	v_mfma_f32_16x16x32_bf16 v[112:115], v[152:155], v[100:103], v[84:87]
	v_mfma_f32_16x16x32_bf16 v[128:131], v[152:155], v[72:75], v[56:59]
	ds_read_b128 v[72:75], v222 offset:36864
	ds_read_b128 v[152:155], v222 offset:37888
	ds_read_b128 v[148:151], v222 offset:39936
	s_waitcnt lgkmcnt(4)
	v_mfma_f32_16x16x32_bf16 v[96:99], v[180:183], v[48:51], v[136:139]
	v_mfma_f32_16x16x32_bf16 v[68:71], v[180:183], v[52:55], v[132:135]
	v_mfma_f32_16x16x32_bf16 v[100:103], v[176:179], v[48:51], v[120:123]
	v_mfma_f32_16x16x32_bf16 v[64:67], v[176:179], v[52:55], v[124:127]
	v_mfma_f32_16x16x32_bf16 v[92:95], v[172:175], v[48:51], v[116:119]
	v_mfma_f32_16x16x32_bf16 v[60:63], v[172:175], v[52:55], v[108:111]
	v_mfma_f32_16x16x32_bf16 v[84:87], v[168:171], v[48:51], v[76:79]
	v_mfma_f32_16x16x32_bf16 v[56:59], v[168:171], v[52:55], v[80:83]
	s_waitcnt lgkmcnt(0)
	v_mfma_f32_16x16x32_bf16 v[88:91], v[72:75], v[48:51], v[164:167]
	v_mfma_f32_16x16x32_bf16 v[72:75], v[72:75], v[52:55], v[160:163]
	v_mfma_f32_16x16x32_bf16 v[104:107], v[152:155], v[48:51], v[104:107]
	v_mfma_f32_16x16x32_bf16 v[76:79], v[152:155], v[52:55], v[156:159]
	v_mfma_f32_16x16x32_bf16 v[108:111], v[226:229], v[48:51], v[144:147]
	v_mfma_f32_16x16x32_bf16 v[80:83], v[226:229], v[52:55], v[140:143]
	v_mfma_f32_16x16x32_bf16 v[48:51], v[148:151], v[48:51], v[112:115]
	v_mfma_f32_16x16x32_bf16 v[52:55], v[148:151], v[52:55], v[128:131]
	s_nop 1
	v_mov_b32_e32 v112, v220
	v_mov_b32_e32 v128, v221
	s_branch .LBB0_1109
.Latt_masked:
	s_cbranch_vccnz .LBB0_1109
	s_add_u32 s84, s86, s68
	s_addc_u32 s85, s87, s69
	s_mov_b32 m0, s13
	s_nop 0
	global_load_lds_dwordx4 v200, s[84:85]
	s_add_i32 m0, s13, 0x1f80
	s_nop 0
	global_load_lds_dwordx4 v200, s[84:85] offset:128
	s_add_i32 m0, s13, 0x3f00
	s_nop 0
	global_load_lds_dwordx4 v200, s[84:85] offset:256
	s_add_u32 s84, s86, s66
	s_addc_u32 s85, s87, s67
	s_add_i32 m0, s13, 0x6000
	s_nop 0
	global_load_lds_dwordx4 v202, s[84:85]
	s_add_i32 m0, s13, 0x7fc0
	s_nop 0
	global_load_lds_dwordx4 v202, s[84:85] offset:64
